# P1 norm loop: next-row X prefetch into spare VGPRs, all 12 gain/scale/shift loads issued up front with one counted wait
# speedup vs baseline: 1.0012x; 1.0012x over previous
.LBB0_87:
	s_mov_b32 s2, 26
	s_ashr_i32 s3, s2, 31
	s_lshl_b64 s[2:3], s[2:3], 3
	s_add_u32 s2, s0, s2
	s_addc_u32 s3, s1, s3
	s_load_dwordx2 s[94:95], s[2:3], 0x0
	s_mov_b32 s2, 27
	s_ashr_i32 s3, s2, 31
	s_lshl_b64 s[2:3], s[2:3], 3
	s_add_u32 s2, s0, s2
	s_addc_u32 s3, s1, s3
	s_load_dwordx2 s[2:3], s[2:3], 0x0
	v_mov_b32_e32 v2, v196
	s_mov_b32 s10, 27
	s_mov_b32 s8, 6
	s_waitcnt lgkmcnt(0)
	v_writelane_b32 v252, s2, 7
	s_mov_b32 s4, 27
	s_nop 0
	v_writelane_b32 v252, s3, 8
	s_mov_b32 s2, s6
	s_mov_b32 s3, s47
	v_writelane_b32 v252, s2, 9
	s_mov_b32 s6, 27
	s_nop 0
	v_writelane_b32 v252, s3, 10
	s_mul_i32 s2, s2, 0x1e000
	v_writelane_b32 v252, s2, 11
	v_readfirstlane_b32 s2, v2
	s_ashr_i32 s2, s2, 6
	v_readlane_b32 s3, v253, 2
	s_add_i32 s2, s2, s3
	s_cmp_gt_i32 s2, 0x83ff
	s_cbranch_scc1 .LBB0_100
	s_ashr_i32 s11, s10, 31
	s_lshl_b64 s[10:11], s[10:11], 3
	s_add_u32 s10, s0, s10
	s_addc_u32 s11, s1, s11
	s_ashr_i32 s9, s8, 31
	s_lshl_b64 s[8:9], s[8:9], 3
	s_add_u32 s8, s0, s8
	s_addc_u32 s9, s1, s9
	s_ashr_i32 s7, s6, 31
	s_lshl_b64 s[6:7], s[6:7], 3
	s_add_u32 s6, s0, s6
	s_addc_u32 s7, s1, s7
	s_load_dwordx2 s[6:7], s[6:7], 0x0
	s_nop 0
	s_load_dwordx2 s[10:11], s[10:11], 0x0
	s_nop 0
	s_load_dwordx2 s[8:9], s[8:9], 0x0
	v_readlane_b32 s3, v252, 11
	v_lshlrev_b32_e32 v0, 2, v2
	s_waitcnt lgkmcnt(0)
	s_add_u32 s3, s6, s3
	s_addc_u32 s5, s7, 0
	s_add_u32 s18, s3, 0x10000
	s_addc_u32 s19, s5, 0
	s_ashr_i32 s5, s4, 31
	s_lshl_b64 s[4:5], s[4:5], 3
	s_add_u32 s4, s0, s4
	s_addc_u32 s5, s1, s5
	v_readlane_b32 s6, v252, 9
	s_load_dwordx2 s[4:5], s[4:5], 0x0
	v_readlane_b32 s7, v252, 10
	s_lshl_b64 s[6:7], s[6:7], 12
	s_add_u32 s6, s8, s6
	v_and_b32_e32 v4, 0xfc, v0
	s_addc_u32 s7, s9, s7
	v_lshlrev_b32_e32 v0, 2, v4
	v_lshl_add_u64 v[34:35], s[6:7], 0, v[0:1]
	v_lshlrev_b32_e32 v0, 1, v4
	s_waitcnt lgkmcnt(0)
	v_lshl_add_u64 v[12:13], s[4:5], 0, v[0:1]
	v_and_b32_e32 v0, 63, v2
	v_or_b32_e32 v6, 0x100, v4
	v_or_b32_e32 v8, 0x200, v4
	v_or_b32_e32 v10, 0x300, v4
	s_mov_b64 s[4:5], 0x3a00000
	v_lshlrev_b32_e32 v0, 3, v0
	v_lshl_add_u64 v[36:37], v[12:13], 0, s[4:5]
	v_lshl_add_u64 v[38:39], s[10:11], 0, v[0:1]
	v_lshlrev_b32_e32 v0, 2, v4
	v_lshlrev_b32_e32 v44, 2, v6
	v_lshlrev_b32_e32 v45, 2, v8
	v_lshlrev_b32_e32 v46, 2, v10
	s_mov_b32 s10, s2
	s_mul_hi_i32 s3, s10, 0x3e0f83e1
	s_lshr_b32 s11, s3, 31
	s_ashr_i32 s3, s3, 11
	s_add_i32 s12, s3, s11
	s_mul_i32 s3, s12, 0x2100
	s_sub_i32 s14, s10, s3
	s_ashr_i32 s13, s12, 31
	s_mov_b32 s15, 0
	s_cmpk_lt_i32 s14, 0x100
	s_cbranch_scc1 .Lnpf_ctx_pre
	s_add_i32 s14, s14, 0xffffff00
	s_lshl_b64 s[10:11], s[12:13], 25
	v_readlane_b32 s12, v252, 3
	v_readlane_b32 s13, v252, 4
	s_branch .Lnpf_join_pre
.Lnpf_ctx_pre:
	s_lshl_b64 s[10:11], s[12:13], 20
	v_readlane_b32 s12, v252, 5
	v_readlane_b32 s13, v252, 6
.Lnpf_join_pre:
	s_lshl_b64 s[14:15], s[14:15], 12
	s_add_u32 s10, s12, s10
	s_addc_u32 s11, s13, s11
	s_add_u32 s10, s10, s14
	s_addc_u32 s11, s11, s15
	global_load_dwordx4 v[212:215], v0, s[10:11]
	global_load_dwordx4 v[216:219], v0, s[10:11] offset:1024
	global_load_dwordx4 v[220:223], v0, s[10:11] offset:2048
	global_load_dwordx4 v[224:227], v0, s[10:11] offset:3072
	s_waitcnt vmcnt(0)
	s_branch .LBB0_91

.LBB0_90:
	s_lshl_b64 s[4:5], s[4:5], 2
	s_add_u32 s4, s18, s4
	s_addc_u32 s5, s19, s5
	s_add_u32 s6, s4, 0x1000
	s_addc_u32 s7, s5, 0
	global_load_dwordx4 v[84:87], v[34:35], off
	global_load_dwordx4 v[100:103], v0, s[6:7]
	global_load_dwordx4 v[152:155], v0, s[4:5]
	global_load_dwordx4 v[88:91], v[34:35], off offset:1024
	global_load_dwordx4 v[104:107], v44, s[6:7]
	global_load_dwordx4 v[156:159], v0, s[4:5] offset:1024
	global_load_dwordx4 v[92:95], v[34:35], off offset:2048
	global_load_dwordx4 v[108:111], v45, s[6:7]
	global_load_dwordx4 v[160:163], v0, s[4:5] offset:2048
	global_load_dwordx4 v[96:99], v[34:35], off offset:3072
	global_load_dwordx4 v[112:115], v46, s[6:7]
	global_load_dwordx4 v[164:167], v0, s[4:5] offset:3072
	s_ashr_i32 s3, s2, 31
	s_lshl_b64 s[8:9], s[2:3], 11
	v_lshl_add_u64 v[32:33], v[36:37], 0, s[8:9]
	s_add_i32 s10, s2, s20
	s_cmp_lt_i32 s10, 0x8400
	s_cselect_b32 s10, s10, s2
	s_mul_hi_i32 s3, s10, 0x3e0f83e1
	s_lshr_b32 s11, s3, 31
	s_ashr_i32 s3, s3, 11
	s_add_i32 s12, s3, s11
	s_mul_i32 s3, s12, 0x2100
	s_sub_i32 s14, s10, s3
	s_ashr_i32 s13, s12, 31
	s_mov_b32 s15, 0
	s_cmpk_lt_i32 s14, 0x100
	s_cbranch_scc1 .Lnpf_ctx_loop
	s_add_i32 s14, s14, 0xffffff00
	s_lshl_b64 s[10:11], s[12:13], 25
	v_readlane_b32 s12, v252, 3
	v_readlane_b32 s13, v252, 4
	s_branch .Lnpf_join_loop

.Lnpf_join_loop:
	s_lshl_b64 s[14:15], s[14:15], 12
	s_add_u32 s10, s12, s10
	s_addc_u32 s11, s13, s11
	s_add_u32 s10, s10, s14
	s_addc_u32 s11, s11, s15
	global_load_dwordx4 v[212:215], v0, s[10:11]
	global_load_dwordx4 v[216:219], v0, s[10:11] offset:1024
	global_load_dwordx4 v[220:223], v0, s[10:11] offset:2048
	global_load_dwordx4 v[224:227], v0, s[10:11] offset:3072
	v_pk_mul_f32 v[30:31], v[14:15], v[14:15]
	v_pk_mul_f32 v[40:41], v[16:17], v[16:17]
	v_pk_fma_f32 v[30:31], v[10:11], v[10:11], v[30:31]
	v_pk_fma_f32 v[40:41], v[12:13], v[12:13], v[40:41]
	v_pk_fma_f32 v[30:31], v[6:7], v[6:7], v[30:31]
	v_pk_fma_f32 v[40:41], v[8:9], v[8:9], v[40:41]
	v_pk_fma_f32 v[30:31], v[2:3], v[2:3], v[30:31]
	v_pk_fma_f32 v[40:41], v[4:5], v[4:5], v[40:41]
	v_and_b32_e32 v47, 64, v197
	v_pk_add_f32 v[30:31], v[30:31], v[40:41]
	v_add_u32_e32 v47, 64, v47
	s_nop 0
	v_add_f32_e32 v30, v30, v31
	v_xor_b32_e32 v42, 1, v197
	v_cmp_lt_i32_e32 vcc, v42, v47
	s_nop 1
	v_cndmask_b32_e32 v42, v197, v42, vcc
	v_lshlrev_b32_e32 v42, 2, v42
	ds_bpermute_b32 v31, v42, v30
	s_waitcnt lgkmcnt(0)
	v_add_f32_e32 v30, v30, v31
	v_xor_b32_e32 v42, 2, v197
	v_cmp_lt_i32_e32 vcc, v42, v47
	s_nop 1
	v_cndmask_b32_e32 v42, v197, v42, vcc
	v_lshlrev_b32_e32 v42, 2, v42
	ds_bpermute_b32 v31, v42, v30
	s_waitcnt lgkmcnt(0)
	v_add_f32_e32 v30, v30, v31
	v_xor_b32_e32 v42, 4, v197
	v_cmp_lt_i32_e32 vcc, v42, v47
	s_nop 1
	v_cndmask_b32_e32 v42, v197, v42, vcc
	v_lshlrev_b32_e32 v42, 2, v42
	ds_bpermute_b32 v31, v42, v30
	s_waitcnt lgkmcnt(0)
	v_add_f32_e32 v30, v30, v31
	v_xor_b32_e32 v42, 8, v197
	v_cmp_lt_i32_e32 vcc, v42, v47
	s_nop 1
	v_cndmask_b32_e32 v42, v197, v42, vcc
	v_lshlrev_b32_e32 v42, 2, v42
	ds_bpermute_b32 v31, v42, v30
	s_waitcnt lgkmcnt(0)
	v_add_f32_e32 v30, v30, v31
	v_xor_b32_e32 v42, 16, v197
	v_cmp_lt_i32_e32 vcc, v42, v47
	s_nop 1
	v_cndmask_b32_e32 v42, v197, v42, vcc
	v_lshlrev_b32_e32 v42, 2, v42
	ds_bpermute_b32 v31, v42, v30
	s_waitcnt lgkmcnt(0)
	v_add_f32_e32 v30, v30, v31
	v_xor_b32_e32 v42, 32, v197
	v_cmp_lt_i32_e32 vcc, v42, v47
	s_nop 1
	v_cndmask_b32_e32 v42, v197, v42, vcc
	v_lshlrev_b32_e32 v42, 2, v42
	ds_bpermute_b32 v31, v42, v30
	s_waitcnt lgkmcnt(0)
	v_add_f32_e32 v30, v30, v31
	v_fmamk_f32 v30, v30, 0x3a800000, v198
	v_rsq_f32_e32 v30, v30
	s_nop 0
	s_waitcnt vmcnt(4)
	v_pk_mul_f32 v[14:15], v[14:15], v[30:31] op_sel_hi:[1,0]
	v_pk_mul_f32 v[16:17], v[16:17], v[30:31] op_sel_hi:[1,0]
	v_pk_add_f32 v[100:101], v[100:101], 1.0 op_sel_hi:[1,0]
	v_pk_add_f32 v[102:103], v[102:103], 1.0 op_sel_hi:[1,0]
	v_pk_mul_f32 v[14:15], v[84:85], v[14:15]
	v_pk_mul_f32 v[16:17], v[86:87], v[16:17]
	v_pk_fma_f32 v[14:15], v[100:101], v[14:15], v[152:153]
	v_pk_fma_f32 v[16:17], v[102:103], v[16:17], v[154:155]
	v_cvt_pk_bf16_f32 v14, v14, v15
	v_cvt_pk_bf16_f32 v15, v16, v17
	global_store_dwordx2 v[32:33], v[14:15], off
	v_pk_mul_f32 v[10:11], v[10:11], v[30:31] op_sel_hi:[1,0]
	v_pk_mul_f32 v[12:13], v[12:13], v[30:31] op_sel_hi:[1,0]
	v_pk_add_f32 v[104:105], v[104:105], 1.0 op_sel_hi:[1,0]
	v_pk_add_f32 v[106:107], v[106:107], 1.0 op_sel_hi:[1,0]
	v_pk_mul_f32 v[10:11], v[88:89], v[10:11]
	v_pk_mul_f32 v[12:13], v[90:91], v[12:13]
	v_pk_fma_f32 v[10:11], v[104:105], v[10:11], v[156:157]
	v_pk_fma_f32 v[12:13], v[106:107], v[12:13], v[158:159]
	v_cvt_pk_bf16_f32 v10, v10, v11
	v_cvt_pk_bf16_f32 v11, v12, v13
	global_store_dwordx2 v[32:33], v[10:11], off offset:512
	v_pk_mul_f32 v[6:7], v[6:7], v[30:31] op_sel_hi:[1,0]
	v_pk_mul_f32 v[8:9], v[8:9], v[30:31] op_sel_hi:[1,0]
	v_pk_add_f32 v[108:109], v[108:109], 1.0 op_sel_hi:[1,0]
	v_pk_add_f32 v[110:111], v[110:111], 1.0 op_sel_hi:[1,0]
	v_pk_mul_f32 v[6:7], v[92:93], v[6:7]
	v_pk_mul_f32 v[8:9], v[94:95], v[8:9]
	v_pk_fma_f32 v[6:7], v[108:109], v[6:7], v[160:161]
	v_pk_fma_f32 v[8:9], v[110:111], v[8:9], v[162:163]
	v_cvt_pk_bf16_f32 v6, v6, v7
	v_cvt_pk_bf16_f32 v7, v8, v9
	global_store_dwordx2 v[32:33], v[6:7], off offset:1024
	v_pk_mul_f32 v[2:3], v[2:3], v[30:31] op_sel_hi:[1,0]
	v_pk_mul_f32 v[4:5], v[4:5], v[30:31] op_sel_hi:[1,0]
	v_pk_add_f32 v[112:113], v[112:113], 1.0 op_sel_hi:[1,0]
	v_pk_add_f32 v[114:115], v[114:115], 1.0 op_sel_hi:[1,0]
	v_pk_mul_f32 v[2:3], v[96:97], v[2:3]
	v_pk_mul_f32 v[4:5], v[98:99], v[4:5]
	v_pk_fma_f32 v[2:3], v[112:113], v[2:3], v[164:165]
	v_pk_fma_f32 v[4:5], v[114:115], v[4:5], v[166:167]
	v_cvt_pk_bf16_f32 v2, v2, v3
	v_cvt_pk_bf16_f32 v3, v4, v5
	global_store_dwordx2 v[32:33], v[2:3], off offset:1536
	s_add_i32 s2, s2, s20
	s_waitcnt vmcnt(4)
	s_cmp_lt_i32 s2, 0x8400
	s_cbranch_scc0 .LBB0_100

.LBB0_95:
	v_mov_b64_e32 v[14:15], v[212:213]
	v_mov_b64_e32 v[16:17], v[214:215]
	v_mov_b64_e32 v[10:11], v[216:217]
	v_mov_b64_e32 v[12:13], v[218:219]
	v_mov_b64_e32 v[6:7], v[220:221]
	v_mov_b64_e32 v[8:9], v[222:223]
	v_mov_b64_e32 v[2:3], v[224:225]
	v_mov_b64_e32 v[4:5], v[226:227]
	v_readlane_b32 s12, v254, 51
	v_readlane_b32 s13, v254, 52
	s_and_b64 s[10:11], s[12:13], s[10:11]
	s_andn2_b64 vcc, exec, s[10:11]
	s_cbranch_vccnz .LBB0_90
	s_lshl_b32 s10, s8, 2
	s_ashr_i32 s7, s6, 31
	s_ashr_i32 s11, s10, 31
	s_lshl_b64 s[12:13], s[6:7], 9
	s_lshl_b64 s[10:11], s[10:11], 17
	s_add_u32 s10, s10, s12
	s_addc_u32 s11, s11, s13
	v_lshl_add_u64 v[40:41], v[38:39], 0, s[10:11]
	s_mov_b64 s[10:11], 0
	s_branch .LBB0_98
